# MLA per-tile LDS-DMA pieces split: three behind the first K reads of step a, three behind those of step b (both under LDS latency); on the full stack
# baseline (speedup 1.0000x reference)
.LBB0_1220:
	s_mov_b32 s51, 32
	s_mov_b64 s[6:7], 0
	s_cmp_gt_i32 s55, 0
	s_cselect_b32 s98, -1, 2
	s_add_i32 s100, s98, s55
	s_add_i32 s98, s93, 2
	s_min_u32 s98, s98, s56
	s_mul_i32 s99, s98, 0x60000
	s_add_u32 s86, s92, s99
	s_addc_u32 s87, s54, 0
	s_lshl_b32 s98, s98, 18
	s_add_u32 s98, s80, s98
	s_mul_i32 s100, s100, 0xb400
	s_addc_u32 s99, s81, 0
	s_add_i32 vcc_lo, s100, 0
	s_and_b64 s[100:101], s[74:75], exec
	s_cselect_b32 s101, s87, s99
	s_cselect_b32 s100, s86, s98
	v_lshl_add_u64 v[238:239], s[100:101], 0, v[150:151]
	s_add_i32 s100, vcc_lo, s38
	s_mov_b32 s101, m0
	s_mov_b32 m0, s100
	s_nop 0
	global_load_lds_dwordx4 v[238:239], off
	s_mov_b32 m0, s101
	s_and_b64 s[100:101], s[76:77], exec
	s_cselect_b32 s101, s87, s99
	s_cselect_b32 s100, s86, s98
	v_lshl_add_u64 v[238:239], s[100:101], 0, v[168:169]
	s_add_i32 s100, vcc_lo, s88
	s_mov_b32 s101, m0
	s_mov_b32 m0, s100
	s_nop 0
	global_load_lds_dwordx4 v[238:239], off
	s_mov_b32 m0, s101
	s_add_i32 vcc_lo, vcc_lo, s90
	v_lshl_add_u64 v[238:239], s[98:99], 0, v[152:153]
	s_mov_b32 s98, m0
	s_mov_b32 m0, vcc_lo
	s_nop 0
	global_load_lds_dwordx4 v[238:239], off
	s_mov_b32 m0, s98
	s_cbranch_execnz .LBB0_1227
.LBB0_1221:
	s_or_b32 s86, s51, s50
	s_cmp_gt_u32 s86, s57
	s_cbranch_scc1 .LBB0_1220
	v_or_b32_e32 v5, s51, v203
	s_movk_i32 s87, 0x190
	v_mad_u32_u24 v5, v5, s87, v3
	ds_read_b128 v[6:9], v5
	ds_read_b128 v[10:13], v5 offset:32
	ds_read_b128 v[14:17], v5 offset:64
	ds_read_b128 v[216:219], v5 offset:96
	ds_read_b128 v[220:223], v5 offset:128
	ds_read_b128 v[224:227], v5 offset:160
	ds_read_b128 v[228:231], v5 offset:192
	ds_read_b128 v[232:235], v5 offset:224
	s_cmp_lg_u32 s51, 0
	s_cbranch_scc1 .Lmla_dmaB
	s_cmp_gt_i32 s55, 0
	s_cselect_b32 s98, -1, 2
	s_add_i32 s100, s98, s55
	s_add_i32 s98, s93, 2
	s_min_u32 s98, s98, s56
	s_mul_i32 s99, s98, 0x60000
	s_add_u32 s86, s92, s99
	s_addc_u32 s87, s54, 0
	s_lshl_b32 s98, s98, 18
	s_add_u32 s98, s80, s98
	s_mul_i32 s100, s100, 0xb400
	s_addc_u32 s99, s81, 0
	s_add_i32 vcc_lo, s100, 0
	s_and_b64 s[100:101], s[30:31], exec
	s_cselect_b32 s101, s87, s99
	s_cselect_b32 s100, s86, s98
	v_lshl_add_u64 v[238:239], s[100:101], 0, v[166:167]
	s_add_i32 s100, vcc_lo, s20
	s_mov_b32 s101, m0
	s_mov_b32 m0, s100
	s_nop 0
	global_load_lds_dwordx4 v[238:239], off
	s_mov_b32 m0, s101
	s_and_b64 s[100:101], s[52:53], exec
	s_cselect_b32 s101, s87, s99
	s_cselect_b32 s100, s86, s98
	v_lshl_add_u64 v[238:239], s[100:101], 0, v[146:147]
	s_add_i32 s100, vcc_lo, s26
	s_mov_b32 s101, m0
	s_mov_b32 m0, s100
	s_nop 0
	global_load_lds_dwordx4 v[238:239], off
	s_mov_b32 m0, s101
	s_and_b64 s[100:101], s[72:73], exec
	s_cselect_b32 s101, s87, s99
	s_cselect_b32 s100, s86, s98
	v_lshl_add_u64 v[238:239], s[100:101], 0, v[148:149]
	s_add_i32 s100, vcc_lo, s36
	s_mov_b32 s101, m0
	s_mov_b32 m0, s100
	s_nop 0
	global_load_lds_dwordx4 v[238:239], off
	s_mov_b32 m0, s101
	s_branch .Lmla_dmadone
.Lmla_dmaB:
	s_cmp_gt_i32 s55, 0
	s_cselect_b32 s98, -1, 2
	s_add_i32 s100, s98, s55
	s_add_i32 s98, s93, 2
	s_min_u32 s98, s98, s56
	s_mul_i32 s99, s98, 0x60000
	s_add_u32 s86, s92, s99
	s_addc_u32 s87, s54, 0
	s_lshl_b32 s98, s98, 18
	s_add_u32 s98, s80, s98
	s_mul_i32 s100, s100, 0xb400
	s_addc_u32 s99, s81, 0
	s_add_i32 vcc_lo, s100, 0
	s_and_b64 s[100:101], s[74:75], exec
	s_cselect_b32 s101, s87, s99
	s_cselect_b32 s100, s86, s98
	v_lshl_add_u64 v[238:239], s[100:101], 0, v[150:151]
	s_add_i32 s100, vcc_lo, s38
	s_mov_b32 s101, m0
	s_mov_b32 m0, s100
	s_nop 0
	global_load_lds_dwordx4 v[238:239], off
	s_mov_b32 m0, s101
	s_and_b64 s[100:101], s[76:77], exec
	s_cselect_b32 s101, s87, s99
	s_cselect_b32 s100, s86, s98
	v_lshl_add_u64 v[238:239], s[100:101], 0, v[168:169]
	s_add_i32 s100, vcc_lo, s88
	s_mov_b32 s101, m0
	s_mov_b32 m0, s100
	s_nop 0
	global_load_lds_dwordx4 v[238:239], off
	s_mov_b32 m0, s101
	s_add_i32 vcc_lo, vcc_lo, s90
	v_lshl_add_u64 v[238:239], s[98:99], 0, v[152:153]
	s_mov_b32 s98, m0
	s_mov_b32 m0, vcc_lo
	s_nop 0
	global_load_lds_dwordx4 v[238:239], off
	s_mov_b32 m0, s98
.Lmla_dmadone:
	s_or_b32 s86, s51, s50
	s_waitcnt lgkmcnt(7)
	v_mfma_f32_32x32x16_bf16 v[82:97], v[6:9], v[98:101], 0
	ds_read_b128 v[6:9], v5 offset:256
	s_waitcnt lgkmcnt(7)
	v_mfma_f32_32x32x16_bf16 v[82:97], v[10:13], v[102:105], v[82:97]
	ds_read_b128 v[10:13], v5 offset:288
	s_waitcnt lgkmcnt(7)
	v_mfma_f32_32x32x16_bf16 v[82:97], v[14:17], v[106:109], v[82:97]
	ds_read_b128 v[14:17], v5 offset:320
	s_waitcnt lgkmcnt(7)
	v_mfma_f32_32x32x16_bf16 v[82:97], v[216:219], v[110:113], v[82:97]
	ds_read_b128 v[216:219], v5 offset:352
	s_waitcnt lgkmcnt(7)
	v_mfma_f32_32x32x16_bf16 v[82:97], v[220:223], v[114:117], v[82:97]
	s_or_b32 s87, s86, 31
	s_cmp_le_u32 s87, s24
	s_waitcnt lgkmcnt(6)
	v_mfma_f32_32x32x16_bf16 v[82:97], v[224:227], v[118:121], v[82:97]
	s_waitcnt lgkmcnt(5)
	v_mfma_f32_32x32x16_bf16 v[82:97], v[228:231], v[122:125], v[82:97]
	s_waitcnt lgkmcnt(4)
	v_mfma_f32_32x32x16_bf16 v[82:97], v[232:235], v[126:129], v[82:97]
	s_waitcnt lgkmcnt(3)
	v_mfma_f32_32x32x16_bf16 v[82:97], v[6:9], v[130:133], v[82:97]
	s_waitcnt lgkmcnt(2)
	v_mfma_f32_32x32x16_bf16 v[82:97], v[10:13], v[134:137], v[82:97]
	s_waitcnt lgkmcnt(1)
	v_mfma_f32_32x32x16_bf16 v[82:97], v[14:17], v[138:141], v[82:97]
	s_waitcnt lgkmcnt(0)
	v_mfma_f32_32x32x16_bf16 v[82:97], v[216:219], v[142:145], v[82:97]
	v_or_b32_e32 v235, s51, v205
	s_movk_i32 s98, 0x140
	v_mad_u32_u24 v235, v235, s98, v4
	ds_read_b64_tr_b16 v[238:239], v235 offset:25600
	ds_read_b64_tr_b16 v[240:241], v235 offset:28160
	ds_read_b64_tr_b16 v[242:243], v235 offset:30720
	ds_read_b64_tr_b16 v[244:245], v235 offset:33280
	ds_read_b64_tr_b16 v[246:247], v235 offset:25664
	ds_read_b64_tr_b16 v[248:249], v235 offset:28224
	s_cbranch_scc1 .LBB0_1224
	v_or_b32_e32 v5, s86, v208
	v_cmp_lt_u32_e32 vcc, v5, v213
	v_or_b32_e32 v6, 2, v5
	s_nop 7
	v_cndmask_b32_e32 v83, v212, v83, vcc
	v_cmp_le_u32_e32 vcc, v5, v213
	s_nop 1
	v_cndmask_b32_e32 v82, v212, v82, vcc
	v_cmp_le_u32_e32 vcc, v6, v213
	v_or_b32_e32 v6, 3, v5
	s_nop 0
	v_cndmask_b32_e32 v84, v212, v84, vcc
	v_cmp_le_u32_e32 vcc, v6, v213
	v_or_b32_e32 v6, 8, v5
	s_nop 0
	v_cndmask_b32_e32 v85, v212, v85, vcc
	v_cmp_le_u32_e32 vcc, v6, v213
	v_or_b32_e32 v6, 9, v5
	s_nop 0
	v_cndmask_b32_e32 v86, v212, v86, vcc
	v_cmp_le_u32_e32 vcc, v6, v213
	v_or_b32_e32 v6, 10, v5
	s_nop 0
	v_cndmask_b32_e32 v87, v212, v87, vcc
	v_cmp_le_u32_e32 vcc, v6, v213
	v_or_b32_e32 v6, 11, v5
	s_nop 0
	v_cndmask_b32_e32 v88, v212, v88, vcc
	v_cmp_le_u32_e32 vcc, v6, v213
	v_or_b32_e32 v6, 16, v5
	s_nop 0
	v_cndmask_b32_e32 v89, v212, v89, vcc
	v_cmp_le_u32_e32 vcc, v6, v213
	v_or_b32_e32 v6, 17, v5
	s_nop 0
	v_cndmask_b32_e32 v90, v212, v90, vcc
	v_cmp_le_u32_e32 vcc, v6, v213
	v_or_b32_e32 v6, 18, v5
	s_nop 0
	v_cndmask_b32_e32 v91, v212, v91, vcc
	v_cmp_le_u32_e32 vcc, v6, v213
	v_or_b32_e32 v6, 19, v5
	s_nop 0
	v_cndmask_b32_e32 v92, v212, v92, vcc
	v_cmp_le_u32_e32 vcc, v6, v213
	v_or_b32_e32 v6, 24, v5
	s_nop 0
	v_cndmask_b32_e32 v93, v212, v93, vcc
	v_cmp_le_u32_e32 vcc, v6, v213
	v_or_b32_e32 v6, 25, v5
	s_nop 0
	v_cndmask_b32_e32 v94, v212, v94, vcc
	v_cmp_le_u32_e32 vcc, v6, v213
	v_or_b32_e32 v6, 26, v5
	v_or_b32_e32 v5, 27, v5
	v_cndmask_b32_e32 v95, v212, v95, vcc
	v_cmp_le_u32_e32 vcc, v6, v213
	s_nop 1
	v_cndmask_b32_e32 v96, v212, v96, vcc
	v_cmp_le_u32_e32 vcc, v5, v213
	s_nop 1
	v_cndmask_b32_e32 v97, v212, v97, vcc
